# mLSTM scan loop: prefetch loads for the next 8-chunk batch issued right after the wait so the batch round trip overlaps the compute block
# speedup vs baseline: 1.0016x; 1.0016x over previous
; __device__ __forceinline__ unsigned cvtpk(float lo, float hi) { f32x2 v = {lo, hi}; bf16x2_t b = __builtin_convertvector(v, bf16x2_t); return __builtin_bit_cast(unsigned, b); }
; __device__ __forceinline__ void ml_scan(const Args& a) {
;     ...
;             for (int c0 = 0; c0 < 256; c0 += 8) {
;                 unsigned kv[8];
; #pragma unroll
;                 for (int i = 0; i < 8; ++i) kv[i] = p[(size_t)(c0 + i) * 8192];
; #pragma unroll
;                 for (int i = 0; i < 8; ++i) {
;                     const float bl = scal[bh * 256 + c0 + i], ml = scal[2048 + bh * 256 + c0 + i];
;                     const float mn = fmaxf(bl + m, ml), dec = expf(bl + m - mn), sc = expf(ml - mn);
;                     p[(size_t)(c0 + i) * 8192] = cvtpk(C0, C1);
;                     C0 = dec * C0 + sc * __uint_as_float(kv[i] << 16); C1 = dec * C1 + sc * __uint_as_float(kv[i] & 0xffff0000u); m = mn;
;                 }
;             }
.LBB0_481:
	v_lshl_add_u64 v[12:13], s[86:87], 0, v[6:7]
	v_add_co_u32_e32 v24, vcc, 0x19000000, v12
	v_lshl_add_u64 v[14:15], s[86:87], 0, v[8:9]
	s_nop 0
	v_addc_co_u32_e32 v25, vcc, 0, v13, vcc
	v_add_co_u32_e32 v48, vcc, 0x19008000, v12
	v_lshl_add_u64 v[26:27], v[14:15], 0, s[6:7]
	s_nop 0
	v_addc_co_u32_e32 v49, vcc, 0, v13, vcc
	v_add_co_u32_e32 v28, vcc, 0x19010000, v12
	v_lshl_add_u64 v[44:45], v[14:15], 0, s[8:9]
	s_nop 0
	v_addc_co_u32_e32 v29, vcc, 0, v13, vcc
	v_add_co_u32_e32 v22, vcc, 0x19018000, v12
	global_load_dword v51, v[24:25], off
	global_load_dword v53, v[48:49], off
	v_addc_co_u32_e32 v23, vcc, 0, v13, vcc
	v_add_co_u32_e32 v20, vcc, 0x19020000, v12
	global_load_dword v55, v[28:29], off
	global_load_dword v57, v[22:23], off
	v_addc_co_u32_e32 v21, vcc, 0, v13, vcc
	v_add_co_u32_e32 v18, vcc, 0x19028000, v12
	v_cvt_pk_bf16_f32 v50, v10, v11
	s_nop 0
	v_addc_co_u32_e32 v19, vcc, 0, v13, vcc
	v_add_co_u32_e32 v16, vcc, 0x19030000, v12
	global_load_dword v59, v[20:21], off
	global_load_dword v60, v[18:19], off
	v_addc_co_u32_e32 v17, vcc, 0, v13, vcc
	v_add_co_u32_e32 v12, vcc, 0x19038000, v12
	s_add_i32 s19, s19, 8
	s_nop 0
	v_addc_co_u32_e32 v13, vcc, 0, v13, vcc
	v_add_co_u32_e32 v32, vcc, s13, v14
	global_load_dword v61, v[16:17], off
	global_load_dword v62, v[12:13], off
	v_addc_co_u32_e32 v33, vcc, 0, v15, vcc
	v_add_co_u32_e32 v14, vcc, s17, v14
	global_load_dwordx4 v[32:35], v[32:33], off
	s_nop 0
	global_load_dwordx4 v[36:39], v[26:27], off offset:16
	v_addc_co_u32_e32 v15, vcc, 0, v15, vcc
	global_load_dwordx4 v[40:43], v[14:15], off
	s_nop 0
	global_load_dwordx4 v[44:47], v[44:45], off offset:16
	v_lshl_add_u64 v[8:9], v[8:9], 0, 32
	global_store_dword v[24:25], v50, off
	v_lshl_add_u64 v[6:7], v[6:7], 0, s[10:11]
	s_cmpk_gt_u32 s19, 0xf7
	s_waitcnt vmcnt(0)
	v_lshl_add_u64 v[82:83], v[24:25], 0, s[10:11]
	global_load_dword v84, v[82:83], off
	v_lshl_add_u64 v[82:83], v[48:49], 0, s[10:11]
	global_load_dword v84, v[82:83], off
	v_lshl_add_u64 v[82:83], v[28:29], 0, s[10:11]
	global_load_dword v84, v[82:83], off
	v_lshl_add_u64 v[82:83], v[22:23], 0, s[10:11]
	global_load_dword v84, v[82:83], off
	v_lshl_add_u64 v[82:83], v[20:21], 0, s[10:11]
	global_load_dword v84, v[82:83], off
	v_lshl_add_u64 v[82:83], v[18:19], 0, s[10:11]
	global_load_dword v84, v[82:83], off
	v_lshl_add_u64 v[82:83], v[16:17], 0, s[10:11]
	global_load_dword v84, v[82:83], off
	v_lshl_add_u64 v[82:83], v[12:13], 0, s[10:11]
	global_load_dword v84, v[82:83], off
	v_lshlrev_b32_e32 v50, 16, v51
	v_and_b32_e32 v51, 0xffff0000, v51
	v_lshlrev_b32_e32 v52, 16, v53
	v_and_b32_e32 v53, 0xffff0000, v53
	v_lshlrev_b32_e32 v54, 16, v55
	v_and_b32_e32 v55, 0xffff0000, v55
	v_lshlrev_b32_e32 v56, 16, v57
	v_and_b32_e32 v57, 0xffff0000, v57
	v_lshlrev_b32_e32 v58, 16, v59
	v_lshlrev_b32_e32 v26, 16, v60
	v_and_b32_e32 v27, 0xffff0000, v60
	v_and_b32_e32 v59, 0xffff0000, v59
	v_lshlrev_b32_e32 v24, 16, v61
	v_and_b32_e32 v25, 0xffff0000, v61
	v_lshlrev_b32_e32 v14, 16, v62
	v_and_b32_e32 v15, 0xffff0000, v62
	v_add_f32_e32 v4, v4, v32
	v_max_f32_e32 v32, v40, v40
	v_max_f32_e32 v32, v4, v32
	v_max_f32_e32 v60, v41, v41
	v_sub_f32_e32 v4, v4, v32
	v_sub_f32_e32 v40, v40, v32
	v_add_f32_e32 v32, v32, v33
	v_mul_f32_e32 v33, 0x3fb8aa3b, v4
	v_mul_f32_e32 v67, 0x3fb8aa3b, v40
	v_max_f32_e32 v60, v32, v60
	v_max_f32_e32 v61, v42, v42
	v_fma_f32 v68, v4, s14, -v33
	v_rndne_f32_e32 v69, v33
	v_fma_f32 v70, v40, s14, -v67
	v_rndne_f32_e32 v71, v67
	v_sub_f32_e32 v72, v32, v60
	v_sub_f32_e32 v41, v41, v60
	v_add_f32_e32 v32, v60, v34
	v_fmac_f32_e32 v68, 0x32a5705f, v4
	v_sub_f32_e32 v33, v33, v69
	v_cvt_i32_f32_e32 v34, v69
	v_fmac_f32_e32 v70, 0x32a5705f, v40
	v_sub_f32_e32 v60, v67, v71
	v_cvt_i32_f32_e32 v67, v71
	v_mul_f32_e32 v69, 0x3fb8aa3b, v72
	v_mul_f32_e32 v71, 0x3fb8aa3b, v41
	v_max_f32_e32 v61, v32, v61
	v_max_f32_e32 v62, v43, v43
	v_add_f32_e32 v33, v33, v68
	v_add_f32_e32 v60, v60, v70
	v_fma_f32 v68, v72, s14, -v69
	v_rndne_f32_e32 v70, v69
	v_fma_f32 v73, v41, s14, -v71
	v_rndne_f32_e32 v74, v71
	v_sub_f32_e32 v75, v32, v61
	v_sub_f32_e32 v42, v42, v61
	v_add_f32_e32 v32, v61, v35
	v_exp_f32_e32 v33, v33
	v_exp_f32_e32 v35, v60
	v_fmac_f32_e32 v68, 0x32a5705f, v72
	v_sub_f32_e32 v60, v69, v70
	v_cvt_i32_f32_e32 v61, v70
	v_fmac_f32_e32 v73, 0x32a5705f, v41
	v_sub_f32_e32 v69, v71, v74
	v_cvt_i32_f32_e32 v70, v74
	v_mul_f32_e32 v71, 0x3fb8aa3b, v75
	v_mul_f32_e32 v74, 0x3fb8aa3b, v42
	v_max_f32_e32 v62, v32, v62
	v_max_f32_e32 v63, v44, v44
	v_add_f32_e32 v60, v60, v68
	v_add_f32_e32 v68, v69, v73
	v_fma_f32 v69, v75, s14, -v71
	v_rndne_f32_e32 v73, v71
	v_fma_f32 v76, v42, s14, -v74
	v_rndne_f32_e32 v77, v74
	v_sub_f32_e32 v78, v32, v62
	v_sub_f32_e32 v43, v43, v62
	v_add_f32_e32 v32, v62, v36
	v_exp_f32_e32 v36, v60
	v_exp_f32_e32 v60, v68
	v_fmac_f32_e32 v69, 0x32a5705f, v75
	v_sub_f32_e32 v62, v71, v73
	v_cvt_i32_f32_e32 v68, v73
	v_fmac_f32_e32 v76, 0x32a5705f, v42
	v_sub_f32_e32 v71, v74, v77
	v_cvt_i32_f32_e32 v73, v77
	v_mul_f32_e32 v74, 0x3fb8aa3b, v78
	v_mul_f32_e32 v77, 0x3fb8aa3b, v43
	v_max_f32_e32 v63, v32, v63
	v_max_f32_e32 v64, v45, v45
	v_add_f32_e32 v62, v62, v69
	v_add_f32_e32 v69, v71, v76
	v_fma_f32 v71, v78, s14, -v74
	v_rndne_f32_e32 v76, v74
	v_fma_f32 v79, v43, s14, -v77
	v_rndne_f32_e32 v80, v77
	v_sub_f32_e32 v81, v32, v63
	v_sub_f32_e32 v44, v44, v63
	v_add_f32_e32 v32, v63, v37
	v_ldexp_f32 v33, v33, v34
	v_ldexp_f32 v34, v35, v67
	v_cmp_ngt_f32_e32 vcc, s15, v40
	v_exp_f32_e32 v35, v62
	v_exp_f32_e32 v37, v69
	v_fmac_f32_e32 v71, 0x32a5705f, v78
	v_sub_f32_e32 v62, v74, v76
	v_cvt_i32_f32_e32 v63, v76
; __device__ __forceinline__ unsigned cvtpk(float lo, float hi) { f32x2 v = {lo, hi}; bf16x2_t b = __builtin_convertvector(v, bf16x2_t); return __builtin_bit_cast(unsigned, b); }
; __device__ __forceinline__ void ml_scan(const Args& a) {
;     ...
;                 for (int i = 0; i < 8; ++i) {
;                     const float bl = scal[bh * 256 + c0 + i], ml = scal[2048 + bh * 256 + c0 + i];
;                     const float mn = fmaxf(bl + m, ml), dec = expf(bl + m - mn), sc = expf(ml - mn);
;                     p[(size_t)(c0 + i) * 8192] = cvtpk(C0, C1);
;                     C0 = dec * C0 + sc * __uint_as_float(kv[i] << 16); C1 = dec * C1 + sc * __uint_as_float(kv[i] & 0xffff0000u); m = mn;
;                 }
;             }
	v_fmac_f32_e32 v79, 0x32a5705f, v43
	v_sub_f32_e32 v67, v77, v80
	v_mul_f32_e32 v74, 0x3fb8aa3b, v81
	v_mul_f32_e32 v76, 0x3fb8aa3b, v44
	v_max_f32_e32 v64, v32, v64
	v_cmp_ngt_f32_e64 s[4:5], s15, v4
	v_max_f32_e32 v65, v46, v46
	v_cvt_i32_f32_e32 v69, v80
	v_cndmask_b32_e64 v33, 0, v33, s[4:5]
	v_cndmask_b32_e32 v34, 0, v34, vcc
	v_cmp_nlt_f32_e32 vcc, s16, v40
	v_add_f32_e32 v40, v62, v71
	v_add_f32_e32 v62, v67, v79
	v_fma_f32 v67, v81, s14, -v74
	v_rndne_f32_e32 v71, v74
	v_fma_f32 v77, v44, s14, -v76
	v_rndne_f32_e32 v79, v76
	v_sub_f32_e32 v80, v32, v64
	v_add_f32_e32 v38, v64, v38
	v_cmp_nlt_f32_e64 s[4:5], s16, v4
	v_sub_f32_e32 v45, v45, v64
	v_cndmask_b32_e32 v32, v31, v34, vcc
	v_cndmask_b32_e64 v4, v31, v33, s[4:5]
	v_ldexp_f32 v34, v36, v61
	v_cmp_ngt_f32_e32 vcc, s15, v72
	v_ldexp_f32 v36, v60, v70
	v_cmp_ngt_f32_e64 s[4:5], s15, v41
	v_exp_f32_e32 v60, v62
	v_fmac_f32_e32 v67, 0x32a5705f, v81
	v_sub_f32_e32 v61, v74, v71
	v_cvt_i32_f32_e32 v62, v71
	v_fmac_f32_e32 v77, 0x32a5705f, v44
	v_sub_f32_e32 v64, v76, v79
	v_mul_f32_e32 v71, 0x3fb8aa3b, v80
	v_max_f32_e32 v65, v38, v65
	v_exp_f32_e32 v40, v40
	v_mul_f32_e32 v74, 0x3fb8aa3b, v45
	v_pk_mul_f32 v[32:33], v[32:33], v[50:51] op_sel_hi:[0,1]
	v_cndmask_b32_e32 v34, 0, v34, vcc
	v_cmp_nlt_f32_e32 vcc, s16, v72
	v_cndmask_b32_e64 v36, 0, v36, s[4:5]
	v_cmp_nlt_f32_e64 s[4:5], s16, v41
	v_add_f32_e32 v41, v61, v67
	v_add_f32_e32 v50, v64, v77
	v_fma_f32 v51, v80, s14, -v71
	v_rndne_f32_e32 v61, v71
	v_sub_f32_e32 v38, v38, v65
	v_max_f32_e32 v66, v47, v47
	v_fma_f32 v64, v45, s14, -v74
	v_rndne_f32_e32 v67, v74
	v_sub_f32_e32 v46, v46, v65
	v_add_f32_e32 v39, v65, v39
	v_pk_fma_f32 v[10:11], v[10:11], v[4:5], v[32:33] op_sel_hi:[1,0,1]
	v_cndmask_b32_e32 v32, v31, v34, vcc
	v_cndmask_b32_e64 v34, v31, v36, s[4:5]
	v_ldexp_f32 v33, v35, v68
	v_cmp_ngt_f32_e32 vcc, s15, v75
	v_ldexp_f32 v36, v37, v73
	v_cmp_ngt_f32_e64 s[4:5], s15, v42
	v_exp_f32_e32 v37, v41
	v_exp_f32_e32 v41, v50
	v_fmac_f32_e32 v51, 0x32a5705f, v80
	v_sub_f32_e32 v50, v71, v61
	v_mul_f32_e32 v68, 0x3fb8aa3b, v38
	v_fmac_f32_e32 v64, 0x32a5705f, v45
	v_sub_f32_e32 v65, v74, v67
	v_mul_f32_e32 v71, 0x3fb8aa3b, v46
	v_max_f32_e32 v4, v39, v66
	v_cvt_pk_bf16_f32 v66, v10, v11
	v_pk_mul_f32 v[34:35], v[34:35], v[52:53] op_sel_hi:[0,1]
	v_cndmask_b32_e32 v33, 0, v33, vcc
	v_cndmask_b32_e64 v36, 0, v36, s[4:5]
	v_cmp_nlt_f32_e64 s[4:5], s16, v42
	v_add_f32_e32 v42, v50, v51
	v_fma_f32 v51, v38, s14, -v68
	v_rndne_f32_e32 v52, v68
	v_cvt_i32_f32_e32 v70, v79
	v_cmp_nlt_f32_e32 vcc, s16, v75
	v_add_f32_e32 v50, v65, v64
	v_rndne_f32_e32 v64, v71
	global_store_dword v[48:49], v66, off
	v_pk_fma_f32 v[10:11], v[10:11], v[32:33], v[34:35] op_sel_hi:[1,0,1]
	v_cndmask_b32_e64 v34, v31, v36, s[4:5]
	v_ldexp_f32 v36, v60, v69
	v_cmp_ngt_f32_e64 s[4:5], s15, v43
	v_fmac_f32_e32 v51, 0x32a5705f, v38
	v_sub_f32_e32 v48, v68, v52
	v_fma_f32 v53, v46, s14, -v71
	v_sub_f32_e32 v39, v39, v4
	v_sub_f32_e32 v47, v47, v4
	v_cndmask_b32_e32 v32, v31, v33, vcc
	v_ldexp_f32 v33, v40, v63
	v_exp_f32_e32 v40, v42
	v_exp_f32_e32 v42, v50
	v_cvt_i32_f32_e32 v49, v52
	v_sub_f32_e32 v50, v71, v64
	v_cvt_i32_f32_e32 v52, v64
	v_cvt_pk_bf16_f32 v64, v10, v11
	v_cndmask_b32_e64 v36, 0, v36, s[4:5]
	v_cmp_nlt_f32_e64 s[4:5], s16, v43
	v_add_f32_e32 v43, v48, v51
	v_cvt_i32_f32_e32 v61, v61
	v_cvt_i32_f32_e32 v67, v67
	v_cmp_ngt_f32_e32 vcc, s15, v78
	v_fmac_f32_e32 v53, 0x32a5705f, v46
	v_mul_f32_e32 v60, 0x3fb8aa3b, v39
	v_mul_f32_e32 v63, 0x3fb8aa3b, v47
	global_store_dword v[28:29], v64, off
	v_ldexp_f32 v29, v37, v62
	v_exp_f32_e32 v37, v43
	v_pk_mul_f32 v[34:35], v[34:35], v[54:55] op_sel_hi:[0,1]
	v_cndmask_b32_e32 v33, 0, v33, vcc
	v_cmp_nlt_f32_e32 vcc, s16, v78
	v_add_f32_e32 v48, v50, v53
	v_rndne_f32_e32 v51, v60
	v_fma_f32 v53, v47, s14, -v63
	v_rndne_f32_e32 v54, v63
	v_fma_f32 v50, v39, s14, -v60
	v_cndmask_b32_e32 v28, v31, v33, vcc
	v_cndmask_b32_e64 v36, v31, v36, s[4:5]
	v_ldexp_f32 v33, v41, v70
	v_cmp_ngt_f32_e32 vcc, s15, v44
	v_exp_f32_e32 v41, v48
	v_sub_f32_e32 v43, v60, v51
	v_cvt_i32_f32_e32 v48, v51
	v_fmac_f32_e32 v53, 0x32a5705f, v47
	v_sub_f32_e32 v51, v63, v54
	v_cmp_ngt_f32_e64 s[4:5], s15, v81
	v_fmac_f32_e32 v50, 0x32a5705f, v39
	v_pk_fma_f32 v[10:11], v[10:11], v[32:33], v[34:35] op_sel_hi:[1,0,1]
	v_cndmask_b32_e64 v29, 0, v29, s[4:5]
	v_cndmask_b32_e32 v35, 0, v33, vcc
	v_cmp_nlt_f32_e32 vcc, s16, v44
	v_add_f32_e32 v44, v51, v53
	v_cmp_nlt_f32_e64 s[4:5], s16, v81
	v_cvt_i32_f32_e32 v54, v54
	v_add_f32_e32 v43, v43, v50
	v_pk_mul_f32 v[32:33], v[36:37], v[56:57] op_sel_hi:[0,1]
	v_cndmask_b32_e64 v34, v31, v29, s[4:5]
	v_cndmask_b32_e32 v36, v31, v35, vcc
	v_ldexp_f32 v29, v40, v61
	v_ldexp_f32 v35, v42, v67
	v_cmp_ngt_f32_e32 vcc, s15, v45
	v_exp_f32_e32 v42, v44
	v_cmp_ngt_f32_e64 s[4:5], s15, v80
	v_cvt_pk_bf16_f32 v50, v10, v11
	v_exp_f32_e32 v40, v43
	v_pk_fma_f32 v[10:11], v[10:11], v[28:29], v[32:33] op_sel_hi:[1,0,1]
	v_cndmask_b32_e64 v28, 0, v29, s[4:5]
	v_cndmask_b32_e32 v29, 0, v35, vcc
	v_cmp_nlt_f32_e32 vcc, s16, v45
	global_store_dword v[22:23], v50, off
	v_pk_mul_f32 v[22:23], v[36:37], v[58:59] op_sel_hi:[0,1]
	v_cmp_nlt_f32_e64 s[4:5], s16, v80
	v_cndmask_b32_e32 v32, v31, v29, vcc
	v_ldexp_f32 v35, v41, v52
	v_cmp_ngt_f32_e32 vcc, s15, v46
	v_cvt_pk_bf16_f32 v33, v10, v11
	v_cndmask_b32_e64 v28, v31, v28, s[4:5]
	v_ldexp_f32 v29, v37, v49
	v_pk_fma_f32 v[10:11], v[10:11], v[34:35], v[22:23] op_sel_hi:[1,0,1]
	v_cmp_ngt_f32_e64 s[4:5], s15, v38
	v_cndmask_b32_e32 v23, 0, v35, vcc
	v_cmp_nlt_f32_e32 vcc, s16, v46
	global_store_dword v[20:21], v33, off
	v_cndmask_b32_e64 v22, 0, v29, s[4:5]
	v_cvt_pk_bf16_f32 v29, v10, v11
	v_pk_mul_f32 v[20:21], v[32:33], v[26:27] op_sel_hi:[0,1]
	v_cmp_nlt_f32_e64 s[4:5], s16, v38
	v_cndmask_b32_e32 v26, v31, v23, vcc
	v_ldexp_f32 v27, v42, v54
	v_cmp_ngt_f32_e32 vcc, s15, v47
	v_cndmask_b32_e64 v22, v31, v22, s[4:5]
	v_ldexp_f32 v23, v40, v48
	v_pk_fma_f32 v[10:11], v[10:11], v[28:29], v[20:21] op_sel_hi:[1,0,1]
	v_cmp_ngt_f32_e64 s[4:5], s15, v39
	v_cndmask_b32_e32 v21, 0, v27, vcc
	v_cmp_nlt_f32_e32 vcc, s16, v47
	global_store_dword v[18:19], v29, off
	v_cndmask_b32_e64 v20, 0, v23, s[4:5]
	v_cvt_pk_bf16_f32 v23, v10, v11
	v_pk_mul_f32 v[18:19], v[26:27], v[24:25] op_sel_hi:[0,1]
	v_cmp_nlt_f32_e64 s[4:5], s16, v39
	v_cndmask_b32_e32 v24, v31, v21, vcc
	v_pk_fma_f32 v[10:11], v[10:11], v[22:23], v[18:19] op_sel_hi:[1,0,1]
	v_cndmask_b32_e64 v20, v31, v20, s[4:5]
	v_pk_mul_f32 v[14:15], v[24:25], v[14:15] op_sel_hi:[0,1]
	global_store_dword v[16:17], v23, off
	v_cvt_pk_bf16_f32 v16, v10, v11
	v_pk_fma_f32 v[10:11], v[10:11], v[20:21], v[14:15] op_sel_hi:[1,0,1]
	global_store_dword v[12:13], v16, off
	s_cbranch_scc0 .LBB0_481
	s_branch .LBB0_466
